# accumulator zero-init at each tile start with 64 v_mov_b64 instead of 128 v_mov_b32 (6 GEMM unit loops), on top of v44
# speedup vs baseline: 1.0034x; 1.0022x over previous
;     __device__ __forceinline__ bool next(int i, Unit& u) const { u.z = 0; return o.tile(i, u); }
;     __device__ __forceinline__ long a_off(const Unit& u) const { return (long)u.pm * tA; }
;     __device__ __forceinline__ long b_off(const Unit& u) const { return (long)u.pn * tB; }
;     __device__ __forceinline__ bool next(int i, Unit& u) const { u.z = i & 1; return o.tile(i >> 1, u); }
;     __device__ __forceinline__ long a_off(const Unit& u) const { return (long)u.pm * 256 * DM * 2 + (long)u.z * 512 * 2; }
;     __device__ __forceinline__ long b_off(const Unit& u) const { return ((long)u.z * 1024 + (long)u.pn * 256) * 512 * 2; }
;     __device__ __forceinline__ bool next(int i, Unit& u) const { u.z = 0; return o.tile(i, u); }
;     __device__ __forceinline__ long a_off(const Unit& u) const { const int ti = u.pm; const int b = ti / 65, i = ti % 65; return ((long)b * SEQ + 254 * i - 2) * DM * 2; }
;     __device__ __forceinline__ long b_off(const Unit& u) const { return (long)u.pn * 256 * DM * 2; }
; template <class Epi, class Sched>
; __device__ __forceinline__ void gemm_phase(LAS unsigned char* lds, const Gemm g, const Sched& S, const Epi& E) {
;     ...
;     for (;;) {
;         const bool has_next = S.next(ui + 1, nxt);
;         const char* nA = has_next ? (const char*)g.A + S.a_off(nxt) : cA; const char* nB = has_next ? (const char*)g.Bt + S.b_off(nxt) : cB;
;         for (int t = 0; t < nt; t += 2) {
;             const bool last = (t == nt - 2);
;             const char* a1 = cA + (size_t)(t + 1) * kstep;
;             const char* a2 = last ? nA : cA + (size_t)(t + 2) * kstep; const char* b2 = last ? nB : cB + (size_t)(t + 2) * kstep;
;     ...
; #pragma unroll
;         for (int a = 0; a < 2; ++a)
; #pragma unroll
;             for (int b = 0; b < 2; ++b)
; #pragma unroll
;                 for (int m = 0; m < 4; ++m)
; #pragma unroll
;                     for (int n = 0; n < 2; ++n) acc[a][b][m][n] = (f32x4){0.f, 0.f, 0.f, 0.f};
;         }
;         cur = nxt; cA = nA; cB = nB; ++ui;
.LBB0_173:
	s_ashr_i32 s15, s14, 31
	s_lshl_b64 s[16:17], s[14:15], 19
	s_add_u32 s16, s90, s16
	s_addc_u32 s17, s91, s17
	s_and_b64 s[18:19], s[40:41], exec
	s_cselect_b32 s15, s17, s21
	s_cselect_b32 s42, s16, s20
	s_ashr_i32 s13, s12, 31
	s_lshl_b64 s[18:19], s[12:13], 19
	v_readlane_b32 s13, v246, 16
	s_add_u32 s18, s13, s18
	v_readlane_b32 s13, v246, 17
	s_addc_u32 s19, s13, s19
	s_and_b64 s[22:23], s[40:41], exec
	s_cselect_b32 s13, s19, s1
	s_cselect_b32 s43, s18, s0
	s_add_u32 s51, s0, 0x100
	s_addc_u32 s54, s1, 0
	s_add_u32 s0, s20, 0x40080
	v_mov_b32_e32 v0, 0
	s_addc_u32 s1, s21, 0
	s_mov_b32 s55, -2
	v_mov_b64_e32 v[0:1], 0
	v_mov_b64_e32 v[2:3], 0
	v_mov_b64_e32 v[4:5], 0
	v_mov_b64_e32 v[6:7], 0
	v_mov_b64_e32 v[8:9], 0
	v_mov_b64_e32 v[10:11], 0
	v_mov_b64_e32 v[12:13], 0
	v_mov_b64_e32 v[14:15], 0
	v_mov_b64_e32 v[16:17], 0
	v_mov_b64_e32 v[18:19], 0
	v_mov_b64_e32 v[20:21], 0
	v_mov_b64_e32 v[22:23], 0
	v_mov_b64_e32 v[24:25], 0
	v_mov_b64_e32 v[26:27], 0
	v_mov_b64_e32 v[28:29], 0
	v_mov_b64_e32 v[30:31], 0
	v_mov_b64_e32 v[36:37], 0
	v_mov_b64_e32 v[38:39], 0
	v_mov_b64_e32 v[48:49], 0
	v_mov_b64_e32 v[50:51], 0
	v_mov_b64_e32 v[56:57], 0
	v_mov_b64_e32 v[58:59], 0
	v_mov_b64_e32 v[60:61], 0
	v_mov_b64_e32 v[62:63], 0
	v_mov_b64_e32 v[64:65], 0
	v_mov_b64_e32 v[66:67], 0
	v_mov_b64_e32 v[68:69], 0
	v_mov_b64_e32 v[70:71], 0
	v_mov_b64_e32 v[72:73], 0
	v_mov_b64_e32 v[74:75], 0
	v_mov_b64_e32 v[76:77], 0
	v_mov_b64_e32 v[78:79], 0
	v_mov_b64_e32 v[80:81], 0
	v_mov_b64_e32 v[82:83], 0
	v_mov_b64_e32 v[84:85], 0
	v_mov_b64_e32 v[86:87], 0
	v_mov_b64_e32 v[88:89], 0
	v_mov_b64_e32 v[90:91], 0
	v_mov_b64_e32 v[92:93], 0
	v_mov_b64_e32 v[94:95], 0
	v_mov_b64_e32 v[98:99], 0
	v_mov_b64_e32 v[100:101], 0
	v_mov_b64_e32 v[102:103], 0
	v_mov_b64_e32 v[104:105], 0
	v_mov_b64_e32 v[106:107], 0
	v_mov_b64_e32 v[108:109], 0
	v_mov_b64_e32 v[110:111], 0
	v_mov_b64_e32 v[112:113], 0
	v_mov_b64_e32 v[114:115], 0
	v_mov_b64_e32 v[116:117], 0
	v_mov_b64_e32 v[118:119], 0
	v_mov_b64_e32 v[120:121], 0
	v_mov_b64_e32 v[122:123], 0
	v_mov_b64_e32 v[124:125], 0
	v_mov_b64_e32 v[126:127], 0
	v_mov_b64_e32 v[128:129], 0
	v_mov_b64_e32 v[130:131], 0
	v_mov_b64_e32 v[132:133], 0
	v_mov_b64_e32 v[134:135], 0
	v_mov_b64_e32 v[136:137], 0
	v_mov_b64_e32 v[138:139], 0
	v_mov_b64_e32 v[140:141], 0
	v_mov_b64_e32 v[142:143], 0
	v_mov_b64_e32 v[144:145], 0

;     __device__ __forceinline__ bool next(int i, Unit& u) const { u.z = 0; return o.tile(i, u); }
;     __device__ __forceinline__ long a_off(const Unit& u) const { return (long)u.pm * tA; }
;     __device__ __forceinline__ long b_off(const Unit& u) const { return (long)u.pn * tB; }
;     __device__ __forceinline__ bool next(int i, Unit& u) const { u.z = i & 1; return o.tile(i >> 1, u); }
;     __device__ __forceinline__ long a_off(const Unit& u) const { return (long)u.pm * 256 * DM * 2 + (long)u.z * 512 * 2; }
;     __device__ __forceinline__ long b_off(const Unit& u) const { return ((long)u.z * 1024 + (long)u.pn * 256) * 512 * 2; }
;     __device__ __forceinline__ bool next(int i, Unit& u) const { u.z = 0; return o.tile(i, u); }
;     __device__ __forceinline__ long a_off(const Unit& u) const { const int ti = u.pm; const int b = ti / 65, i = ti % 65; return ((long)b * SEQ + 254 * i - 2) * DM * 2; }
;     __device__ __forceinline__ long b_off(const Unit& u) const { return (long)u.pn * 256 * DM * 2; }
; template <class Epi, class Sched>
; __device__ __forceinline__ void gemm_phase(LAS unsigned char* lds, const Gemm g, const Sched& S, const Epi& E) {
;     ...
;     for (;;) {
;         const bool has_next = S.next(ui + 1, nxt);
;         const char* nA = has_next ? (const char*)g.A + S.a_off(nxt) : cA; const char* nB = has_next ? (const char*)g.Bt + S.b_off(nxt) : cB;
;         for (int t = 0; t < nt; t += 2) {
;             const bool last = (t == nt - 2);
;             const char* a1 = cA + (size_t)(t + 1) * kstep;
;             const char* a2 = last ? nA : cA + (size_t)(t + 2) * kstep; const char* b2 = last ? nB : cB + (size_t)(t + 2) * kstep;
;     ...
; #pragma unroll
;         for (int a = 0; a < 2; ++a)
; #pragma unroll
;             for (int b = 0; b < 2; ++b)
; #pragma unroll
;                 for (int m = 0; m < 4; ++m)
; #pragma unroll
;                     for (int n = 0; n < 2; ++n) acc[a][b][m][n] = (f32x4){0.f, 0.f, 0.f, 0.f};
;         }
;         cur = nxt; cA = nA; cB = nB; ++ui;
.LBB0_878:
	s_ashr_i32 s15, s14, 31
	s_lshl_b64 s[16:17], s[14:15], 19
	s_add_u32 s16, s54, s16
	s_addc_u32 s17, s55, s17
	s_and_b64 s[18:19], s[46:47], exec
	s_cselect_b32 s15, s17, s21
	s_cselect_b32 s49, s16, s20
	s_ashr_i32 s13, s12, 31
	s_lshl_b64 s[18:19], s[12:13], 19
	s_add_u32 s18, s40, s18
	s_addc_u32 s19, s41, s19
	s_and_b64 s[22:23], s[46:47], exec
	s_cselect_b32 s13, s19, s1
	s_cselect_b32 s50, s18, s0
	s_add_u32 s51, s0, 0x100
	s_addc_u32 s56, s1, 0
	s_add_u32 s0, s20, 0x40080
	v_mov_b32_e32 v0, 0
	s_addc_u32 s1, s21, 0
	s_mov_b32 s57, -2
	s_waitcnt lgkmcnt(0)
	v_mov_b64_e32 v[0:1], 0
	v_mov_b64_e32 v[2:3], 0
	v_mov_b64_e32 v[4:5], 0
	v_mov_b64_e32 v[6:7], 0
	v_mov_b64_e32 v[8:9], 0
	v_mov_b64_e32 v[10:11], 0
	v_mov_b64_e32 v[12:13], 0
	v_mov_b64_e32 v[14:15], 0
	v_mov_b64_e32 v[16:17], 0
	v_mov_b64_e32 v[18:19], 0
	v_mov_b64_e32 v[20:21], 0
	v_mov_b64_e32 v[22:23], 0
	v_mov_b64_e32 v[24:25], 0
	v_mov_b64_e32 v[26:27], 0
	v_mov_b64_e32 v[28:29], 0
	v_mov_b64_e32 v[30:31], 0
	v_mov_b64_e32 v[32:33], 0
	v_mov_b64_e32 v[34:35], 0
	v_mov_b64_e32 v[36:37], 0
	v_mov_b64_e32 v[38:39], 0
	v_mov_b64_e32 v[40:41], 0
	v_mov_b64_e32 v[42:43], 0
	v_mov_b64_e32 v[44:45], 0
	v_mov_b64_e32 v[46:47], 0
	v_mov_b64_e32 v[48:49], 0
	v_mov_b64_e32 v[50:51], 0
	v_mov_b64_e32 v[52:53], 0
	v_mov_b64_e32 v[54:55], 0
	v_mov_b64_e32 v[56:57], 0
	v_mov_b64_e32 v[58:59], 0
	v_mov_b64_e32 v[60:61], 0
	v_mov_b64_e32 v[62:63], 0
	v_mov_b64_e32 v[64:65], 0
	v_mov_b64_e32 v[66:67], 0
	v_mov_b64_e32 v[68:69], 0
	v_mov_b64_e32 v[70:71], 0
	v_mov_b64_e32 v[72:73], 0
	v_mov_b64_e32 v[74:75], 0
	v_mov_b64_e32 v[76:77], 0
	v_mov_b64_e32 v[78:79], 0
	v_mov_b64_e32 v[80:81], 0
	v_mov_b64_e32 v[82:83], 0
	v_mov_b64_e32 v[84:85], 0
	v_mov_b64_e32 v[86:87], 0
	v_mov_b64_e32 v[88:89], 0
	v_mov_b64_e32 v[90:91], 0
	v_mov_b64_e32 v[92:93], 0
	v_mov_b64_e32 v[94:95], 0
	v_mov_b64_e32 v[98:99], 0
	v_mov_b64_e32 v[100:101], 0
	v_mov_b64_e32 v[102:103], 0
	v_mov_b64_e32 v[104:105], 0
	v_mov_b64_e32 v[106:107], 0
	v_mov_b64_e32 v[108:109], 0
	v_mov_b64_e32 v[110:111], 0
	v_mov_b64_e32 v[112:113], 0
	v_mov_b64_e32 v[114:115], 0
	v_mov_b64_e32 v[116:117], 0
	v_mov_b64_e32 v[122:123], 0
	v_mov_b64_e32 v[124:125], 0
	v_mov_b64_e32 v[130:131], 0
	v_mov_b64_e32 v[132:133], 0
	v_mov_b64_e32 v[142:143], 0
	v_mov_b64_e32 v[144:145], 0

;     __device__ __forceinline__ bool next(int i, Unit& u) const { u.z = 0; return o.tile(i, u); }
;     __device__ __forceinline__ long a_off(const Unit& u) const { return (long)u.pm * tA; }
;     __device__ __forceinline__ long b_off(const Unit& u) const { return (long)u.pn * tB; }
;     __device__ __forceinline__ bool next(int i, Unit& u) const { u.z = i & 1; return o.tile(i >> 1, u); }
;     __device__ __forceinline__ long a_off(const Unit& u) const { return (long)u.pm * 256 * DM * 2 + (long)u.z * 512 * 2; }
;     __device__ __forceinline__ long b_off(const Unit& u) const { return ((long)u.z * 1024 + (long)u.pn * 256) * 512 * 2; }
;     __device__ __forceinline__ bool next(int i, Unit& u) const { u.z = 0; return o.tile(i, u); }
;     __device__ __forceinline__ long a_off(const Unit& u) const { const int ti = u.pm; const int b = ti / 65, i = ti % 65; return ((long)b * SEQ + 254 * i - 2) * DM * 2; }
;     __device__ __forceinline__ long b_off(const Unit& u) const { return (long)u.pn * 256 * DM * 2; }
; template <class Epi, class Sched>
; __device__ __forceinline__ void gemm_phase(LAS unsigned char* lds, const Gemm g, const Sched& S, const Epi& E) {
;     ...
;     for (;;) {
;         const bool has_next = S.next(ui + 1, nxt);
;         const char* nA = has_next ? (const char*)g.A + S.a_off(nxt) : cA; const char* nB = has_next ? (const char*)g.Bt + S.b_off(nxt) : cB;
;         for (int t = 0; t < nt; t += 2) {
;             const bool last = (t == nt - 2);
;             const char* a1 = cA + (size_t)(t + 1) * kstep;
;             const char* a2 = last ? nA : cA + (size_t)(t + 2) * kstep; const char* b2 = last ? nB : cB + (size_t)(t + 2) * kstep;
;     ...
; #pragma unroll
;         for (int a = 0; a < 2; ++a)
; #pragma unroll
;             for (int b = 0; b < 2; ++b)
; #pragma unroll
;                 for (int m = 0; m < 4; ++m)
; #pragma unroll
;                     for (int n = 0; n < 2; ++n) acc[a][b][m][n] = (f32x4){0.f, 0.f, 0.f, 0.f};
;         }
;         cur = nxt; cA = nA; cB = nB; ++ui;
.LBB0_923:
	s_ashr_i32 s15, s14, 31
	s_lshl_b64 s[16:17], s[14:15], 19
	s_add_u32 s16, s54, s16
	s_addc_u32 s17, s55, s17
	s_and_b64 s[18:19], s[46:47], exec
	s_cselect_b32 s15, s17, s21
	s_cselect_b32 s49, s16, s20
	s_ashr_i32 s13, s12, 31
	s_lshl_b64 s[18:19], s[12:13], 19
	s_add_u32 s18, s40, s18
	s_addc_u32 s19, s41, s19
	s_and_b64 s[22:23], s[46:47], exec
	s_cselect_b32 s13, s19, s1
	s_cselect_b32 s50, s18, s0
	s_add_u32 s51, s0, 0x100
	s_addc_u32 s56, s1, 0
	s_add_u32 s0, s20, 0x40080
	v_mov_b32_e32 v0, 0
	s_addc_u32 s1, s21, 0
	s_mov_b32 s57, -2
	s_waitcnt lgkmcnt(0)
	v_mov_b64_e32 v[0:1], 0
	v_mov_b64_e32 v[2:3], 0
	v_mov_b64_e32 v[4:5], 0
	v_mov_b64_e32 v[6:7], 0
	v_mov_b64_e32 v[8:9], 0
	v_mov_b64_e32 v[10:11], 0
	v_mov_b64_e32 v[12:13], 0
	v_mov_b64_e32 v[14:15], 0
	v_mov_b64_e32 v[16:17], 0
	v_mov_b64_e32 v[18:19], 0
	v_mov_b64_e32 v[20:21], 0
	v_mov_b64_e32 v[22:23], 0
	v_mov_b64_e32 v[24:25], 0
	v_mov_b64_e32 v[26:27], 0
	v_mov_b64_e32 v[28:29], 0
	v_mov_b64_e32 v[30:31], 0
	v_mov_b64_e32 v[32:33], 0
	v_mov_b64_e32 v[34:35], 0
	v_mov_b64_e32 v[36:37], 0
	v_mov_b64_e32 v[38:39], 0
	v_mov_b64_e32 v[40:41], 0
	v_mov_b64_e32 v[42:43], 0
	v_mov_b64_e32 v[44:45], 0
	v_mov_b64_e32 v[46:47], 0
	v_mov_b64_e32 v[48:49], 0
	v_mov_b64_e32 v[50:51], 0
	v_mov_b64_e32 v[52:53], 0
	v_mov_b64_e32 v[54:55], 0
	v_mov_b64_e32 v[56:57], 0
	v_mov_b64_e32 v[58:59], 0
	v_mov_b64_e32 v[60:61], 0
	v_mov_b64_e32 v[62:63], 0
	v_mov_b64_e32 v[64:65], 0
	v_mov_b64_e32 v[66:67], 0
	v_mov_b64_e32 v[68:69], 0
	v_mov_b64_e32 v[70:71], 0
	v_mov_b64_e32 v[72:73], 0
	v_mov_b64_e32 v[74:75], 0
	v_mov_b64_e32 v[76:77], 0
	v_mov_b64_e32 v[78:79], 0
	v_mov_b64_e32 v[80:81], 0
	v_mov_b64_e32 v[82:83], 0
	v_mov_b64_e32 v[84:85], 0
	v_mov_b64_e32 v[86:87], 0
	v_mov_b64_e32 v[88:89], 0
	v_mov_b64_e32 v[90:91], 0
	v_mov_b64_e32 v[92:93], 0
	v_mov_b64_e32 v[94:95], 0
	v_mov_b64_e32 v[98:99], 0
	v_mov_b64_e32 v[100:101], 0
	v_mov_b64_e32 v[102:103], 0
	v_mov_b64_e32 v[104:105], 0
	v_mov_b64_e32 v[106:107], 0
	v_mov_b64_e32 v[108:109], 0
	v_mov_b64_e32 v[110:111], 0
	v_mov_b64_e32 v[112:113], 0
	v_mov_b64_e32 v[114:115], 0
	v_mov_b64_e32 v[116:117], 0
	v_mov_b64_e32 v[118:119], 0
	v_mov_b64_e32 v[120:121], 0
	v_mov_b64_e32 v[122:123], 0
	v_mov_b64_e32 v[124:125], 0
	v_mov_b64_e32 v[126:127], 0
	v_mov_b64_e32 v[128:129], 0

;     __device__ __forceinline__ bool next(int i, Unit& u) const { u.z = 0; return o.tile(i, u); }
;     __device__ __forceinline__ long a_off(const Unit& u) const { return (long)u.pm * tA; }
;     __device__ __forceinline__ long b_off(const Unit& u) const { return (long)u.pn * tB; }
;     __device__ __forceinline__ bool next(int i, Unit& u) const { u.z = i & 1; return o.tile(i >> 1, u); }
;     __device__ __forceinline__ long a_off(const Unit& u) const { return (long)u.pm * 256 * DM * 2 + (long)u.z * 512 * 2; }
;     __device__ __forceinline__ long b_off(const Unit& u) const { return ((long)u.z * 1024 + (long)u.pn * 256) * 512 * 2; }
;     __device__ __forceinline__ bool next(int i, Unit& u) const { u.z = 0; return o.tile(i, u); }
;     __device__ __forceinline__ long a_off(const Unit& u) const { const int ti = u.pm; const int b = ti / 65, i = ti % 65; return ((long)b * SEQ + 254 * i - 2) * DM * 2; }
;     __device__ __forceinline__ long b_off(const Unit& u) const { return (long)u.pn * 256 * DM * 2; }
; template <class Epi, class Sched>
; __device__ __forceinline__ void gemm_phase(LAS unsigned char* lds, const Gemm g, const Sched& S, const Epi& E) {
;     ...
;     for (;;) {
;         const bool has_next = S.next(ui + 1, nxt);
;         const char* nA = has_next ? (const char*)g.A + S.a_off(nxt) : cA; const char* nB = has_next ? (const char*)g.Bt + S.b_off(nxt) : cB;
;         for (int t = 0; t < nt; t += 2) {
;             const bool last = (t == nt - 2);
;             const char* a1 = cA + (size_t)(t + 1) * kstep;
;             const char* a2 = last ? nA : cA + (size_t)(t + 2) * kstep; const char* b2 = last ? nB : cB + (size_t)(t + 2) * kstep;
;     ...
; #pragma unroll
;         for (int a = 0; a < 2; ++a)
; #pragma unroll
;             for (int b = 0; b < 2; ++b)
; #pragma unroll
;                 for (int m = 0; m < 4; ++m)
; #pragma unroll
;                     for (int n = 0; n < 2; ++n) acc[a][b][m][n] = (f32x4){0.f, 0.f, 0.f, 0.f};
;         }
;         cur = nxt; cA = nA; cB = nB; ++ui;
.LBB0_1024:
	s_ashr_i32 s9, s8, 31
	s_lshl_b64 s[10:11], s[8:9], 19
	s_add_u32 s10, s90, s10
	s_addc_u32 s11, s91, s11
	s_and_b64 s[12:13], s[46:47], exec
	s_cselect_b32 s9, s11, s19
	s_cselect_b32 s17, s10, s18
	s_ashr_i32 s3, s2, 31
	s_lshl_b64 s[12:13], s[2:3], 19
	v_readlane_b32 s3, v246, 26
	s_add_u32 s12, s3, s12
	v_readlane_b32 s3, v246, 27
	s_addc_u32 s13, s3, s13
	s_and_b64 s[20:21], s[46:47], exec
	s_cselect_b32 s3, s13, s15
	s_cselect_b32 s23, s12, s14
	s_add_u32 s48, s14, 0x100
	s_addc_u32 s49, s15, 0
	s_add_u32 s14, s18, 0x40080
	v_mov_b32_e32 v20, 0
	s_addc_u32 s15, s19, 0
	s_mov_b32 s50, -2
	v_mov_b64_e32 v[0:1], 0
	v_mov_b64_e32 v[2:3], 0
	v_mov_b64_e32 v[4:5], 0
	v_mov_b64_e32 v[6:7], 0
	v_mov_b64_e32 v[8:9], 0
	v_mov_b64_e32 v[10:11], 0
	v_mov_b64_e32 v[12:13], 0
	v_mov_b64_e32 v[14:15], 0
	v_mov_b64_e32 v[16:17], 0
	v_mov_b64_e32 v[18:19], 0
	v_mov_b64_e32 v[20:21], 0
	v_mov_b64_e32 v[22:23], 0
	v_mov_b64_e32 v[24:25], 0
	v_mov_b64_e32 v[26:27], 0
	v_mov_b64_e32 v[28:29], 0
	v_mov_b64_e32 v[30:31], 0
	v_mov_b64_e32 v[32:33], 0
	v_mov_b64_e32 v[34:35], 0
	v_mov_b64_e32 v[36:37], 0
	v_mov_b64_e32 v[38:39], 0
	v_mov_b64_e32 v[40:41], 0
	v_mov_b64_e32 v[42:43], 0
	v_mov_b64_e32 v[44:45], 0
	v_mov_b64_e32 v[46:47], 0
	v_mov_b64_e32 v[48:49], 0
	v_mov_b64_e32 v[50:51], 0
	v_mov_b64_e32 v[52:53], 0
	v_mov_b64_e32 v[54:55], 0
	v_mov_b64_e32 v[56:57], 0
	v_mov_b64_e32 v[58:59], 0
	v_mov_b64_e32 v[60:61], 0
	v_mov_b64_e32 v[62:63], 0
	v_mov_b64_e32 v[64:65], 0
	v_mov_b64_e32 v[66:67], 0
	v_mov_b64_e32 v[68:69], 0
	v_mov_b64_e32 v[70:71], 0
	v_mov_b64_e32 v[72:73], 0
	v_mov_b64_e32 v[74:75], 0
	v_mov_b64_e32 v[76:77], 0
	v_mov_b64_e32 v[78:79], 0
	v_mov_b64_e32 v[114:115], 0
	v_mov_b64_e32 v[116:117], 0
	v_mov_b64_e32 v[118:119], 0
	v_mov_b64_e32 v[120:121], 0
	v_mov_b64_e32 v[122:123], 0
	v_mov_b64_e32 v[124:125], 0
	v_mov_b64_e32 v[128:129], 0
	v_mov_b64_e32 v[130:131], 0
	v_mov_b64_e32 v[132:133], 0
	v_mov_b64_e32 v[134:135], 0
	v_mov_b64_e32 v[136:137], 0
	v_mov_b64_e32 v[138:139], 0
	v_mov_b64_e32 v[140:141], 0
	v_mov_b64_e32 v[142:143], 0
	v_mov_b64_e32 v[144:145], 0
	v_mov_b64_e32 v[146:147], 0
	v_mov_b64_e32 v[148:149], 0
	v_mov_b64_e32 v[150:151], 0
	v_mov_b64_e32 v[152:153], 0
	v_mov_b64_e32 v[154:155], 0
	v_mov_b64_e32 v[156:157], 0
	v_mov_b64_e32 v[158:159], 0
	v_mov_b64_e32 v[160:161], 0
	v_mov_b64_e32 v[162:163], 0

;     __device__ __forceinline__ bool next(int i, Unit& u) const { u.z = 0; return o.tile(i, u); }
;     __device__ __forceinline__ long a_off(const Unit& u) const { return (long)u.pm * tA; }
;     __device__ __forceinline__ long b_off(const Unit& u) const { return (long)u.pn * tB; }
;     __device__ __forceinline__ bool next(int i, Unit& u) const { u.z = i & 1; return o.tile(i >> 1, u); }
;     __device__ __forceinline__ long a_off(const Unit& u) const { return (long)u.pm * 256 * DM * 2 + (long)u.z * 512 * 2; }
;     __device__ __forceinline__ long b_off(const Unit& u) const { return ((long)u.z * 1024 + (long)u.pn * 256) * 512 * 2; }
;     __device__ __forceinline__ bool next(int i, Unit& u) const { u.z = 0; return o.tile(i, u); }
;     __device__ __forceinline__ long a_off(const Unit& u) const { const int ti = u.pm; const int b = ti / 65, i = ti % 65; return ((long)b * SEQ + 254 * i - 2) * DM * 2; }
;     __device__ __forceinline__ long b_off(const Unit& u) const { return (long)u.pn * 256 * DM * 2; }
; template <class Epi, class Sched>
; __device__ __forceinline__ void gemm_phase(LAS unsigned char* lds, const Gemm g, const Sched& S, const Epi& E) {
;     ...
;     for (;;) {
;         const bool has_next = S.next(ui + 1, nxt);
;         const char* nA = has_next ? (const char*)g.A + S.a_off(nxt) : cA; const char* nB = has_next ? (const char*)g.Bt + S.b_off(nxt) : cB;
;         for (int t = 0; t < nt; t += 2) {
;             const bool last = (t == nt - 2);
;             const char* a1 = cA + (size_t)(t + 1) * kstep;
;             const char* a2 = last ? nA : cA + (size_t)(t + 2) * kstep; const char* b2 = last ? nB : cB + (size_t)(t + 2) * kstep;
;     ...
; #pragma unroll
;         for (int a = 0; a < 2; ++a)
; #pragma unroll
;             for (int b = 0; b < 2; ++b)
; #pragma unroll
;                 for (int m = 0; m < 4; ++m)
; #pragma unroll
;                     for (int n = 0; n < 2; ++n) acc[a][b][m][n] = (f32x4){0.f, 0.f, 0.f, 0.f};
;         }
;         cur = nxt; cA = nA; cB = nB; ++ui;
.LBB0_1241:
	s_add_u32 s45, s14, 0x100
	v_mov_b32_e32 v0, 0
	s_addc_u32 s48, s15, 0
	s_mov_b32 s49, -2
	v_mov_b64_e32 v[0:1], 0
	v_mov_b64_e32 v[2:3], 0
	v_mov_b64_e32 v[4:5], 0
	v_mov_b64_e32 v[6:7], 0
	v_mov_b64_e32 v[8:9], 0
	v_mov_b64_e32 v[10:11], 0
	v_mov_b64_e32 v[12:13], 0
	v_mov_b64_e32 v[14:15], 0
	v_mov_b64_e32 v[16:17], 0
	v_mov_b64_e32 v[18:19], 0
	v_mov_b64_e32 v[20:21], 0
	v_mov_b64_e32 v[22:23], 0
	v_mov_b64_e32 v[24:25], 0
	v_mov_b64_e32 v[26:27], 0
	v_mov_b64_e32 v[28:29], 0
	v_mov_b64_e32 v[30:31], 0
	v_mov_b64_e32 v[32:33], 0
	v_mov_b64_e32 v[34:35], 0
	v_mov_b64_e32 v[36:37], 0
	v_mov_b64_e32 v[38:39], 0
	v_mov_b64_e32 v[40:41], 0
	v_mov_b64_e32 v[42:43], 0
	v_mov_b64_e32 v[44:45], 0
	v_mov_b64_e32 v[46:47], 0
	v_mov_b64_e32 v[48:49], 0
	v_mov_b64_e32 v[50:51], 0
	v_mov_b64_e32 v[52:53], 0
	v_mov_b64_e32 v[54:55], 0
	v_mov_b64_e32 v[56:57], 0
	v_mov_b64_e32 v[58:59], 0
	v_mov_b64_e32 v[60:61], 0
	v_mov_b64_e32 v[62:63], 0
	v_mov_b64_e32 v[64:65], 0
	v_mov_b64_e32 v[66:67], 0
	v_mov_b64_e32 v[68:69], 0
	v_mov_b64_e32 v[70:71], 0
	v_mov_b64_e32 v[72:73], 0
	v_mov_b64_e32 v[74:75], 0
	v_mov_b64_e32 v[76:77], 0
	v_mov_b64_e32 v[78:79], 0
	v_mov_b64_e32 v[80:81], 0
	v_mov_b64_e32 v[82:83], 0
	v_mov_b64_e32 v[84:85], 0
	v_mov_b64_e32 v[86:87], 0
	v_mov_b64_e32 v[88:89], 0
	v_mov_b64_e32 v[90:91], 0
	v_mov_b64_e32 v[92:93], 0
	v_mov_b64_e32 v[94:95], 0
	v_mov_b64_e32 v[98:99], 0
	v_mov_b64_e32 v[100:101], 0
	v_mov_b64_e32 v[102:103], 0
	v_mov_b64_e32 v[104:105], 0
	v_mov_b64_e32 v[106:107], 0
	v_mov_b64_e32 v[108:109], 0
	v_mov_b64_e32 v[110:111], 0
	v_mov_b64_e32 v[112:113], 0
	v_mov_b64_e32 v[114:115], 0
	v_mov_b64_e32 v[116:117], 0
	v_mov_b64_e32 v[118:119], 0
	v_mov_b64_e32 v[120:121], 0
	v_mov_b64_e32 v[122:123], 0
	v_mov_b64_e32 v[124:125], 0
	v_mov_b64_e32 v[126:127], 0
	v_mov_b64_e32 v[128:129], 0

;     __device__ __forceinline__ bool next(int i, Unit& u) const { u.z = 0; return o.tile(i, u); }
;     __device__ __forceinline__ long a_off(const Unit& u) const { return (long)u.pm * tA; }
;     __device__ __forceinline__ long b_off(const Unit& u) const { return (long)u.pn * tB; }
;     __device__ __forceinline__ bool next(int i, Unit& u) const { u.z = i & 1; return o.tile(i >> 1, u); }
;     __device__ __forceinline__ long a_off(const Unit& u) const { return (long)u.pm * 256 * DM * 2 + (long)u.z * 512 * 2; }
;     __device__ __forceinline__ long b_off(const Unit& u) const { return ((long)u.z * 1024 + (long)u.pn * 256) * 512 * 2; }
;     __device__ __forceinline__ bool next(int i, Unit& u) const { u.z = 0; return o.tile(i, u); }
;     __device__ __forceinline__ long a_off(const Unit& u) const { const int ti = u.pm; const int b = ti / 65, i = ti % 65; return ((long)b * SEQ + 254 * i - 2) * DM * 2; }
;     __device__ __forceinline__ long b_off(const Unit& u) const { return (long)u.pn * 256 * DM * 2; }
; template <class Epi, class Sched>
; __device__ __forceinline__ void gemm_phase(LAS unsigned char* lds, const Gemm g, const Sched& S, const Epi& E) {
;     ...
;     for (;;) {
;         const bool has_next = S.next(ui + 1, nxt);
;         const char* nA = has_next ? (const char*)g.A + S.a_off(nxt) : cA; const char* nB = has_next ? (const char*)g.Bt + S.b_off(nxt) : cB;
;         for (int t = 0; t < nt; t += 2) {
;             const bool last = (t == nt - 2);
;             const char* a1 = cA + (size_t)(t + 1) * kstep;
;             const char* a2 = last ? nA : cA + (size_t)(t + 2) * kstep; const char* b2 = last ? nB : cB + (size_t)(t + 2) * kstep;
;     ...
; #pragma unroll
;         for (int a = 0; a < 2; ++a)
; #pragma unroll
;             for (int b = 0; b < 2; ++b)
; #pragma unroll
;                 for (int m = 0; m < 4; ++m)
; #pragma unroll
;                     for (int n = 0; n < 2; ++n) acc[a][b][m][n] = (f32x4){0.f, 0.f, 0.f, 0.f};
;         }
;         cur = nxt; cA = nA; cB = nB; ++ui;
.LBB0_1274:
	s_add_u32 s49, s18, 0x100
	v_mov_b32_e32 v0, 0
	s_addc_u32 s50, s19, 0
	s_mov_b32 s51, -2
	s_waitcnt lgkmcnt(0)
	v_mov_b64_e32 v[0:1], 0
	v_mov_b64_e32 v[2:3], 0
	v_mov_b64_e32 v[4:5], 0
	v_mov_b64_e32 v[6:7], 0
	v_mov_b64_e32 v[8:9], 0
	v_mov_b64_e32 v[10:11], 0
	v_mov_b64_e32 v[12:13], 0
	v_mov_b64_e32 v[14:15], 0
	v_mov_b64_e32 v[16:17], 0
	v_mov_b64_e32 v[18:19], 0
	v_mov_b64_e32 v[20:21], 0
	v_mov_b64_e32 v[22:23], 0
	v_mov_b64_e32 v[24:25], 0
	v_mov_b64_e32 v[26:27], 0
	v_mov_b64_e32 v[28:29], 0
	v_mov_b64_e32 v[30:31], 0
	v_mov_b64_e32 v[32:33], 0
	v_mov_b64_e32 v[34:35], 0
	v_mov_b64_e32 v[36:37], 0
	v_mov_b64_e32 v[38:39], 0
	v_mov_b64_e32 v[40:41], 0
	v_mov_b64_e32 v[42:43], 0
	v_mov_b64_e32 v[44:45], 0
	v_mov_b64_e32 v[46:47], 0
	v_mov_b64_e32 v[48:49], 0
	v_mov_b64_e32 v[50:51], 0
	v_mov_b64_e32 v[52:53], 0
	v_mov_b64_e32 v[54:55], 0
	v_mov_b64_e32 v[56:57], 0
	v_mov_b64_e32 v[58:59], 0
	v_mov_b64_e32 v[60:61], 0
	v_mov_b64_e32 v[62:63], 0
	v_mov_b64_e32 v[64:65], 0
	v_mov_b64_e32 v[66:67], 0
	v_mov_b64_e32 v[68:69], 0
	v_mov_b64_e32 v[70:71], 0
	v_mov_b64_e32 v[72:73], 0
	v_mov_b64_e32 v[74:75], 0
	v_mov_b64_e32 v[76:77], 0
	v_mov_b64_e32 v[78:79], 0
	v_mov_b64_e32 v[80:81], 0
	v_mov_b64_e32 v[82:83], 0
	v_mov_b64_e32 v[84:85], 0
	v_mov_b64_e32 v[86:87], 0
	v_mov_b64_e32 v[88:89], 0
	v_mov_b64_e32 v[90:91], 0
	v_mov_b64_e32 v[92:93], 0
	v_mov_b64_e32 v[94:95], 0
	v_mov_b64_e32 v[98:99], 0
	v_mov_b64_e32 v[100:101], 0
	v_mov_b64_e32 v[102:103], 0
	v_mov_b64_e32 v[104:105], 0
	v_mov_b64_e32 v[106:107], 0
	v_mov_b64_e32 v[108:109], 0
	v_mov_b64_e32 v[110:111], 0
	v_mov_b64_e32 v[112:113], 0
	v_mov_b64_e32 v[114:115], 0
	v_mov_b64_e32 v[116:117], 0
	v_mov_b64_e32 v[122:123], 0
	v_mov_b64_e32 v[124:125], 0
	v_mov_b64_e32 v[130:131], 0
	v_mov_b64_e32 v[132:133], 0
	v_mov_b64_e32 v[142:143], 0
	v_mov_b64_e32 v[144:145], 0
